# as v6 plus nt on read-once x rows, sample K/V cache and sample scan state loads
# speedup vs baseline: 1.0208x; 1.0093x over previous
.LBB0_125:
	s_cmpk_gt_i32 s14, 0x21ff
	s_mov_b64 s[4:5], -1
	s_cbranch_scc0 .LBB0_129
	s_add_i32 s6, s14, 0xffffde00
	s_lshl_b64 s[4:5], s[6:7], 14
	s_waitcnt lgkmcnt(0)
	v_lshl_add_u64 v[40:41], v[24:25], 0, s[4:5]
	v_add_co_u32_e32 v66, vcc, s38, v40
	global_load_dwordx4 v[2:5], v[40:41], off nt
	global_load_dwordx4 v[6:9], v[40:41], off offset:1024 nt
	global_load_dwordx4 v[10:13], v[40:41], off offset:2048 nt
	global_load_dwordx4 v[14:17], v[40:41], off offset:3072 nt
	v_addc_co_u32_e32 v67, vcc, 0, v41, vcc
	global_load_dwordx4 v[18:21], v[66:67], off offset:-4096 nt
	v_add_co_u32_e32 v50, vcc, s33, v40
	s_lshl_b64 s[4:5], s[6:7], 13
	s_nop 0
	v_addc_co_u32_e32 v51, vcc, 0, v41, vcc
	global_load_dwordx4 v[42:45], v[50:51], off offset:1024 nt
	global_load_dwordx4 v[46:49], v[50:51], off offset:2048 nt
	s_nop 0
	global_load_dwordx4 v[50:53], v[50:51], off offset:3072 nt
	s_nop 0
	global_load_dwordx4 v[54:57], v[66:67], off nt
	global_load_dwordx4 v[58:61], v[66:67], off offset:1024 nt
	global_load_dwordx4 v[62:65], v[66:67], off offset:2048 nt
	s_nop 0
	global_load_dwordx4 v[66:69], v[66:67], off offset:3072 nt
	v_add_co_u32_e32 v40, vcc, s39, v40
	s_waitcnt vmcnt(11)
	v_mul_f32_e32 v39, v3, v3
	v_addc_co_u32_e32 v41, vcc, 0, v41, vcc
	global_load_dwordx4 v[70:73], v[40:41], off nt
	global_load_dwordx4 v[74:77], v[40:41], off offset:1024 nt
	global_load_dwordx4 v[78:81], v[40:41], off offset:2048 nt
	global_load_dwordx4 v[82:85], v[40:41], off offset:3072 nt
	v_mul_f32_e32 v40, v5, v5
	s_waitcnt vmcnt(14)
	v_mul_f32_e32 v41, v7, v7
	v_mul_f32_e32 v86, v9, v9
	s_waitcnt vmcnt(13)
	v_mul_f32_e32 v87, v11, v11
	v_mul_f32_e32 v88, v13, v13
	v_fmac_f32_e32 v39, v2, v2
	v_fmac_f32_e32 v40, v4, v4
	v_fmac_f32_e32 v41, v6, v6
	v_fmac_f32_e32 v86, v8, v8
	s_waitcnt vmcnt(12)
	v_mul_f32_e32 v89, v15, v15
	v_mul_f32_e32 v90, v17, v17
	v_fmac_f32_e32 v87, v10, v10
	v_fmac_f32_e32 v88, v12, v12
	v_add_f32_e32 v39, v39, v40
	v_add_f32_e32 v40, v41, v86
	v_fmac_f32_e32 v89, v14, v14
	v_fmac_f32_e32 v90, v16, v16
	s_waitcnt vmcnt(11)
	v_mul_f32_e32 v91, v19, v19
	v_mul_f32_e32 v92, v21, v21
	v_add_f32_e32 v41, v87, v88
	v_add_f32_e32 v39, v39, v40
	s_waitcnt vmcnt(10)
	v_mul_f32_e32 v93, v43, v43
	v_mul_f32_e32 v94, v45, v45
	v_add_f32_e32 v86, v89, v90
	v_fmac_f32_e32 v91, v18, v18
	v_fmac_f32_e32 v92, v20, v20
	v_add_f32_e32 v39, v39, v41
	s_waitcnt vmcnt(9)
	v_mul_f32_e32 v95, v47, v47
	v_mul_f32_e32 v96, v49, v49
	v_fmac_f32_e32 v93, v42, v42
	v_fmac_f32_e32 v94, v44, v44
	v_add_f32_e32 v40, v91, v92
	v_add_f32_e32 v39, v39, v86
	s_waitcnt vmcnt(8)
	v_mul_f32_e32 v97, v51, v51
	v_mul_f32_e32 v98, v53, v53
	v_fmac_f32_e32 v95, v46, v46
	v_fmac_f32_e32 v96, v48, v48
	v_add_f32_e32 v87, v93, v94
	v_add_f32_e32 v39, v39, v40
	s_waitcnt vmcnt(7)
	v_mul_f32_e32 v99, v55, v55
	v_mul_f32_e32 v100, v57, v57
	v_fmac_f32_e32 v97, v50, v50
	v_fmac_f32_e32 v98, v52, v52
	v_add_f32_e32 v88, v95, v96
	v_add_f32_e32 v39, v39, v87
	s_waitcnt vmcnt(6)
	v_mul_f32_e32 v101, v59, v59
	v_mul_f32_e32 v102, v61, v61
	v_fmac_f32_e32 v99, v54, v54
	v_fmac_f32_e32 v100, v56, v56
	v_add_f32_e32 v89, v97, v98
	v_add_f32_e32 v39, v39, v88
	s_waitcnt vmcnt(5)
	v_mul_f32_e32 v103, v63, v63
	v_mul_f32_e32 v104, v65, v65
	v_fmac_f32_e32 v101, v58, v58
	v_fmac_f32_e32 v102, v60, v60
	v_add_f32_e32 v90, v99, v100
	v_add_f32_e32 v39, v39, v89
	v_fmac_f32_e32 v103, v62, v62
	v_fmac_f32_e32 v104, v64, v64
	v_add_f32_e32 v91, v101, v102
	v_add_f32_e32 v39, v39, v90
	s_waitcnt vmcnt(4)
	v_mul_f32_e32 v40, v67, v67
	v_mul_f32_e32 v41, v69, v69
	v_add_f32_e32 v92, v103, v104
	v_add_f32_e32 v39, v39, v91
	v_fmac_f32_e32 v40, v66, v66
	v_fmac_f32_e32 v41, v68, v68
	v_add_f32_e32 v39, v39, v92
	v_add_f32_e32 v40, v40, v41
	v_add_f32_e32 v39, v39, v40
	v_cmp_lt_i32_e32 vcc, v33, v32
	v_lshl_add_u64 v[86:87], v[26:27], 0, s[4:5]
	v_cvt_pk_bf16_f32 v2, v2, v3
	v_cvt_pk_bf16_f32 v3, v4, v5
	global_store_dwordx2 v[86:87], v[2:3], off
	v_cvt_pk_bf16_f32 v2, v6, v7
	s_waitcnt vmcnt(4)
	v_mul_f32_e32 v40, v71, v71
	v_mul_f32_e32 v41, v73, v73
	v_fmac_f32_e32 v40, v70, v70
	v_fmac_f32_e32 v41, v72, v72
	v_add_f32_e32 v40, v40, v41
	v_add_f32_e32 v39, v39, v40
	s_waitcnt vmcnt(3)
	v_mul_f32_e32 v40, v75, v75
	v_mul_f32_e32 v41, v77, v77
	v_fmac_f32_e32 v40, v74, v74
	v_fmac_f32_e32 v41, v76, v76
	v_add_f32_e32 v40, v40, v41
	v_add_f32_e32 v39, v39, v40
	s_waitcnt vmcnt(2)
	v_mul_f32_e32 v40, v79, v79
	v_mul_f32_e32 v41, v81, v81
	v_fmac_f32_e32 v40, v78, v78
	v_fmac_f32_e32 v41, v80, v80
	v_add_f32_e32 v40, v40, v41
	v_add_f32_e32 v39, v39, v40
	s_waitcnt vmcnt(1)
	v_mul_f32_e32 v40, v83, v83
	v_mul_f32_e32 v41, v85, v85
	v_fmac_f32_e32 v40, v82, v82
	v_fmac_f32_e32 v41, v84, v84
	v_add_f32_e32 v40, v40, v41
	v_add_f32_e32 v39, v39, v40
	v_cndmask_b32_e32 v40, v31, v33, vcc
	v_lshlrev_b32_e32 v40, 2, v40
	ds_bpermute_b32 v40, v40, v39
	v_cmp_lt_i32_e32 vcc, v34, v32
	v_cvt_pk_bf16_f32 v3, v8, v9
	global_store_dwordx2 v[86:87], v[2:3], off offset:512
	v_cvt_pk_bf16_f32 v2, v10, v11
	s_waitcnt lgkmcnt(0)
	v_add_f32_e32 v39, v39, v40
	v_cndmask_b32_e32 v40, v31, v34, vcc
	v_lshlrev_b32_e32 v40, 2, v40
	ds_bpermute_b32 v40, v40, v39
	v_cmp_lt_i32_e32 vcc, v35, v32
	v_cvt_pk_bf16_f32 v3, v12, v13
	global_store_dwordx2 v[86:87], v[2:3], off offset:1024
	v_cvt_pk_bf16_f32 v2, v14, v15
	s_waitcnt lgkmcnt(0)
	v_add_f32_e32 v39, v39, v40
	v_cndmask_b32_e32 v40, v31, v35, vcc
	v_lshlrev_b32_e32 v40, 2, v40
	ds_bpermute_b32 v40, v40, v39
	v_cmp_lt_i32_e32 vcc, v36, v32
	v_cvt_pk_bf16_f32 v3, v16, v17
	global_store_dwordx2 v[86:87], v[2:3], off offset:1536
	v_cvt_pk_bf16_f32 v2, v18, v19
	s_waitcnt lgkmcnt(0)
	v_add_f32_e32 v39, v39, v40
	v_cndmask_b32_e32 v40, v31, v36, vcc
	v_lshlrev_b32_e32 v40, 2, v40
	ds_bpermute_b32 v40, v40, v39
	v_cmp_lt_i32_e32 vcc, v37, v32
	v_cvt_pk_bf16_f32 v3, v20, v21
	global_store_dwordx2 v[86:87], v[2:3], off offset:2048
	v_cvt_pk_bf16_f32 v2, v42, v43
	s_waitcnt lgkmcnt(0)
	v_add_f32_e32 v39, v39, v40
	v_cndmask_b32_e32 v40, v31, v37, vcc
	v_lshlrev_b32_e32 v40, 2, v40
	ds_bpermute_b32 v40, v40, v39
	v_cvt_pk_bf16_f32 v3, v44, v45
	v_cmp_lt_i32_e32 vcc, v38, v32
	global_store_dwordx2 v[86:87], v[2:3], off offset:2560
	v_cvt_pk_bf16_f32 v2, v46, v47
	v_cvt_pk_bf16_f32 v3, v48, v49
	s_waitcnt lgkmcnt(0)
	v_add_f32_e32 v39, v39, v40
	v_cndmask_b32_e32 v40, v31, v38, vcc
	global_store_dwordx2 v[86:87], v[2:3], off offset:3072
	v_cvt_pk_bf16_f32 v2, v50, v51
	v_cvt_pk_bf16_f32 v3, v52, v53
	v_add_co_u32_e32 v4, vcc, s33, v86
	global_store_dwordx2 v[86:87], v[2:3], off offset:3584
	v_cvt_pk_bf16_f32 v2, v54, v55
	v_cvt_pk_bf16_f32 v3, v56, v57
	v_addc_co_u32_e32 v5, vcc, 0, v87, vcc
	global_store_dwordx2 v[4:5], v[2:3], off
	v_cvt_pk_bf16_f32 v2, v58, v59
	v_cvt_pk_bf16_f32 v3, v60, v61
	v_lshlrev_b32_e32 v40, 2, v40
	global_store_dwordx2 v[4:5], v[2:3], off offset:512
	v_cvt_pk_bf16_f32 v2, v62, v63
	v_cvt_pk_bf16_f32 v3, v64, v65
	ds_bpermute_b32 v40, v40, v39
	global_store_dwordx2 v[4:5], v[2:3], off offset:1024
	v_cvt_pk_bf16_f32 v2, v66, v67
	v_cvt_pk_bf16_f32 v3, v68, v69
	global_store_dwordx2 v[4:5], v[2:3], off offset:1536
	v_cvt_pk_bf16_f32 v2, v70, v71
	v_cvt_pk_bf16_f32 v3, v72, v73
	global_store_dwordx2 v[4:5], v[2:3], off offset:2048
	v_cvt_pk_bf16_f32 v2, v74, v75
	v_cvt_pk_bf16_f32 v3, v76, v77
	global_store_dwordx2 v[4:5], v[2:3], off offset:2560
	v_cvt_pk_bf16_f32 v2, v78, v79
	v_cvt_pk_bf16_f32 v3, v80, v81
	global_store_dwordx2 v[4:5], v[2:3], off offset:3072
	v_cvt_pk_bf16_f32 v2, v82, v83
	v_cvt_pk_bf16_f32 v3, v84, v85
	global_store_dwordx2 v[4:5], v[2:3], off offset:3584
	s_and_saveexec_b64 s[16:17], s[2:3]
	s_cbranch_execz .LBB0_128
	s_waitcnt lgkmcnt(0)
	v_add_f32_e32 v2, v39, v40
	v_fmamk_f32 v2, v2, 0x39800000, v1
	v_mul_f32_e32 v3, 0x4f800000, v2
	v_cmp_gt_f32_e32 vcc, s40, v2
	s_nop 1
	v_cndmask_b32_e32 v2, v2, v3, vcc
	v_sqrt_f32_e32 v3, v2
	s_nop 0
	v_add_u32_e32 v4, -1, v3
	v_fma_f32 v6, -v4, v3, v2
	v_add_u32_e32 v5, 1, v3
	v_cmp_ge_f32_e64 s[4:5], 0, v6
	s_nop 1
	v_cndmask_b32_e64 v4, v3, v4, s[4:5]
	v_fma_f32 v3, -v5, v3, v2
	v_cmp_lt_f32_e64 s[4:5], 0, v3
	s_nop 1
	v_cndmask_b32_e64 v3, v4, v5, s[4:5]
	v_mul_f32_e32 v4, 0x37800000, v3
	v_cndmask_b32_e32 v3, v3, v4, vcc
	v_cmp_class_f32_e32 vcc, v2, v30
	s_nop 1
	v_cndmask_b32_e32 v2, v3, v2, vcc
	v_div_scale_f32 v3, s[4:5], v2, v2, 1.0
	v_rcp_f32_e32 v4, v3
	s_lshl_b64 s[4:5], s[6:7], 2
	s_add_u32 s4, s12, s4
	s_addc_u32 s5, s13, s5
	v_fma_f32 v5, -v3, v4, 1.0
	v_fmac_f32_e32 v4, v5, v4
	v_div_scale_f32 v5, vcc, 1.0, v2, 1.0
	v_mul_f32_e32 v6, v5, v4
	v_fma_f32 v7, -v3, v6, v5
	v_fmac_f32_e32 v6, v7, v4
	v_fma_f32 v3, -v3, v6, v5
	v_div_fmas_f32 v3, v3, v4, v6
	v_div_fixup_f32 v2, v3, v2, 1.0
	global_store_dword v23, v2, s[4:5]

.LBB0_132:
	s_waitcnt lgkmcnt(0)
	v_lshl_add_u64 v[40:41], s[4:5], 0, v[22:23]
	v_add_co_u32_e32 v66, vcc, s38, v40
	global_load_dwordx4 v[2:5], v22, s[4:5] nt
	global_load_dwordx4 v[6:9], v22, s[4:5] offset:1024 nt
	global_load_dwordx4 v[10:13], v22, s[4:5] offset:2048 nt
	global_load_dwordx4 v[14:17], v22, s[4:5] offset:3072 nt
	v_addc_co_u32_e32 v67, vcc, 0, v41, vcc
	global_load_dwordx4 v[18:21], v[66:67], off offset:-4096 nt
	v_add_co_u32_e32 v50, vcc, s33, v40
	s_lshl_b64 s[4:5], s[16:17], 13
	s_nop 0
	v_addc_co_u32_e32 v51, vcc, 0, v41, vcc
	global_load_dwordx4 v[42:45], v[50:51], off offset:1024 nt
	global_load_dwordx4 v[46:49], v[50:51], off offset:2048 nt
	s_nop 0
	global_load_dwordx4 v[50:53], v[50:51], off offset:3072 nt
	s_nop 0
	global_load_dwordx4 v[54:57], v[66:67], off nt
	global_load_dwordx4 v[58:61], v[66:67], off offset:1024 nt
	global_load_dwordx4 v[62:65], v[66:67], off offset:2048 nt
	s_nop 0
	global_load_dwordx4 v[66:69], v[66:67], off offset:3072 nt
	v_add_co_u32_e32 v40, vcc, s39, v40
	s_waitcnt vmcnt(11)
	v_mul_f32_e32 v39, v3, v3
	v_addc_co_u32_e32 v41, vcc, 0, v41, vcc
	global_load_dwordx4 v[70:73], v[40:41], off nt
	global_load_dwordx4 v[74:77], v[40:41], off offset:1024 nt
	global_load_dwordx4 v[78:81], v[40:41], off offset:2048 nt
	global_load_dwordx4 v[82:85], v[40:41], off offset:3072 nt
	v_mul_f32_e32 v40, v5, v5
	s_waitcnt vmcnt(14)
	v_mul_f32_e32 v41, v7, v7
	v_mul_f32_e32 v86, v9, v9
	s_waitcnt vmcnt(13)
	v_mul_f32_e32 v87, v11, v11
	v_mul_f32_e32 v88, v13, v13
	v_fmac_f32_e32 v39, v2, v2
	v_fmac_f32_e32 v40, v4, v4
	v_fmac_f32_e32 v41, v6, v6
	v_fmac_f32_e32 v86, v8, v8
	s_waitcnt vmcnt(12)
	v_mul_f32_e32 v89, v15, v15
	v_mul_f32_e32 v90, v17, v17
	v_fmac_f32_e32 v87, v10, v10
	v_fmac_f32_e32 v88, v12, v12
	v_add_f32_e32 v39, v39, v40
	v_add_f32_e32 v40, v41, v86
	v_fmac_f32_e32 v89, v14, v14
	v_fmac_f32_e32 v90, v16, v16
	v_add_f32_e32 v41, v87, v88
	s_waitcnt vmcnt(11)
	v_mul_f32_e32 v87, v19, v19
	v_mul_f32_e32 v88, v21, v21
	v_add_f32_e32 v39, v39, v40
	v_add_f32_e32 v86, v89, v90
	s_waitcnt vmcnt(10)
	v_mul_f32_e32 v89, v43, v43
	v_mul_f32_e32 v90, v45, v45
	v_fmac_f32_e32 v87, v18, v18
	v_fmac_f32_e32 v88, v20, v20
	v_add_f32_e32 v39, v39, v41
	s_waitcnt vmcnt(9)
	v_mul_f32_e32 v91, v47, v47
	v_mul_f32_e32 v92, v49, v49
	v_fmac_f32_e32 v89, v42, v42
	v_fmac_f32_e32 v90, v44, v44
	v_add_f32_e32 v40, v87, v88
	v_add_f32_e32 v39, v39, v86
	s_waitcnt vmcnt(8)
	v_mul_f32_e32 v93, v51, v51
	v_mul_f32_e32 v94, v53, v53
	v_fmac_f32_e32 v91, v46, v46
	v_fmac_f32_e32 v92, v48, v48
	v_add_f32_e32 v41, v89, v90
	v_add_f32_e32 v39, v39, v40
	s_waitcnt vmcnt(7)
	v_mul_f32_e32 v95, v55, v55
	v_mul_f32_e32 v96, v57, v57
	v_fmac_f32_e32 v93, v50, v50
	v_fmac_f32_e32 v94, v52, v52
	v_add_f32_e32 v87, v91, v92
	v_add_f32_e32 v39, v39, v41
	s_waitcnt vmcnt(6)
	v_mul_f32_e32 v97, v59, v59
	v_mul_f32_e32 v98, v61, v61
	v_fmac_f32_e32 v95, v54, v54
	v_fmac_f32_e32 v96, v56, v56
	v_add_f32_e32 v88, v93, v94
	v_add_f32_e32 v39, v39, v87
	s_waitcnt vmcnt(5)
	v_mul_f32_e32 v99, v63, v63
	v_mul_f32_e32 v100, v65, v65
	v_fmac_f32_e32 v97, v58, v58
	v_fmac_f32_e32 v98, v60, v60
	v_add_f32_e32 v89, v95, v96
	v_add_f32_e32 v39, v39, v88
	v_fmac_f32_e32 v99, v62, v62
	v_fmac_f32_e32 v100, v64, v64
	v_add_f32_e32 v90, v97, v98
	v_add_f32_e32 v39, v39, v89
	v_add_f32_e32 v39, v39, v90
	v_add_f32_e32 v40, v99, v100
	v_add_f32_e32 v39, v39, v40
	s_waitcnt vmcnt(4)
	v_mul_f32_e32 v40, v67, v67
	v_mul_f32_e32 v41, v69, v69
	v_fmac_f32_e32 v40, v66, v66
	v_fmac_f32_e32 v41, v68, v68
	v_add_f32_e32 v40, v40, v41
	v_add_f32_e32 v39, v39, v40
	v_cmp_lt_i32_e32 vcc, v33, v32
	v_lshl_add_u64 v[86:87], v[28:29], 0, s[4:5]
	v_cvt_pk_bf16_f32 v2, v2, v3
	v_cvt_pk_bf16_f32 v3, v4, v5
	global_store_dwordx2 v[86:87], v[2:3], off
	v_cvt_pk_bf16_f32 v2, v6, v7
	s_waitcnt vmcnt(4)
	v_mul_f32_e32 v40, v71, v71
	v_mul_f32_e32 v41, v73, v73
	v_fmac_f32_e32 v40, v70, v70
	v_fmac_f32_e32 v41, v72, v72
	v_add_f32_e32 v40, v40, v41
	v_add_f32_e32 v39, v39, v40
	s_waitcnt vmcnt(3)
	v_mul_f32_e32 v40, v75, v75
	v_mul_f32_e32 v41, v77, v77
	v_fmac_f32_e32 v40, v74, v74
	v_fmac_f32_e32 v41, v76, v76
	v_add_f32_e32 v40, v40, v41
	v_add_f32_e32 v39, v39, v40
	s_waitcnt vmcnt(2)
	v_mul_f32_e32 v40, v79, v79
	v_mul_f32_e32 v41, v81, v81
	v_fmac_f32_e32 v40, v78, v78
	v_fmac_f32_e32 v41, v80, v80
	v_add_f32_e32 v40, v40, v41
	v_add_f32_e32 v39, v39, v40
	s_waitcnt vmcnt(1)
	v_mul_f32_e32 v40, v83, v83
	v_mul_f32_e32 v41, v85, v85
	v_fmac_f32_e32 v40, v82, v82
	v_fmac_f32_e32 v41, v84, v84
	v_add_f32_e32 v40, v40, v41
	v_add_f32_e32 v39, v39, v40
	v_cndmask_b32_e32 v40, v31, v33, vcc
	v_lshlrev_b32_e32 v40, 2, v40
	ds_bpermute_b32 v40, v40, v39
	v_cmp_lt_i32_e32 vcc, v34, v32
	v_cvt_pk_bf16_f32 v3, v8, v9
	global_store_dwordx2 v[86:87], v[2:3], off offset:512
	v_cvt_pk_bf16_f32 v2, v10, v11
	s_waitcnt lgkmcnt(0)
	v_add_f32_e32 v39, v39, v40
	v_cndmask_b32_e32 v40, v31, v34, vcc
	v_lshlrev_b32_e32 v40, 2, v40
	ds_bpermute_b32 v40, v40, v39
	v_cmp_lt_i32_e32 vcc, v35, v32
	v_cvt_pk_bf16_f32 v3, v12, v13
	global_store_dwordx2 v[86:87], v[2:3], off offset:1024
	v_cvt_pk_bf16_f32 v2, v14, v15
	s_waitcnt lgkmcnt(0)
	v_add_f32_e32 v39, v39, v40
	v_cndmask_b32_e32 v40, v31, v35, vcc
	v_lshlrev_b32_e32 v40, 2, v40
	ds_bpermute_b32 v40, v40, v39
	v_cmp_lt_i32_e32 vcc, v36, v32
	v_cvt_pk_bf16_f32 v3, v16, v17
	global_store_dwordx2 v[86:87], v[2:3], off offset:1536
	v_cvt_pk_bf16_f32 v2, v18, v19
	s_waitcnt lgkmcnt(0)
	v_add_f32_e32 v39, v39, v40
	v_cndmask_b32_e32 v40, v31, v36, vcc
	v_lshlrev_b32_e32 v40, 2, v40
	ds_bpermute_b32 v40, v40, v39
	v_cmp_lt_i32_e32 vcc, v37, v32
	v_cvt_pk_bf16_f32 v3, v20, v21
	global_store_dwordx2 v[86:87], v[2:3], off offset:2048
	v_cvt_pk_bf16_f32 v2, v42, v43
	s_waitcnt lgkmcnt(0)
	v_add_f32_e32 v39, v39, v40
	v_cndmask_b32_e32 v40, v31, v37, vcc
	v_lshlrev_b32_e32 v40, 2, v40
	ds_bpermute_b32 v40, v40, v39
	v_cvt_pk_bf16_f32 v3, v44, v45
	v_cmp_lt_i32_e32 vcc, v38, v32
	global_store_dwordx2 v[86:87], v[2:3], off offset:2560
	v_cvt_pk_bf16_f32 v2, v46, v47
	v_cvt_pk_bf16_f32 v3, v48, v49
	s_waitcnt lgkmcnt(0)
	v_add_f32_e32 v39, v39, v40
	v_cndmask_b32_e32 v40, v31, v38, vcc
	global_store_dwordx2 v[86:87], v[2:3], off offset:3072
	v_cvt_pk_bf16_f32 v2, v50, v51
	v_cvt_pk_bf16_f32 v3, v52, v53
	v_add_co_u32_e32 v4, vcc, s33, v86
	global_store_dwordx2 v[86:87], v[2:3], off offset:3584
	v_cvt_pk_bf16_f32 v2, v54, v55
	v_cvt_pk_bf16_f32 v3, v56, v57
	v_addc_co_u32_e32 v5, vcc, 0, v87, vcc
	global_store_dwordx2 v[4:5], v[2:3], off
	v_cvt_pk_bf16_f32 v2, v58, v59
	v_cvt_pk_bf16_f32 v3, v60, v61
	v_lshlrev_b32_e32 v40, 2, v40
	global_store_dwordx2 v[4:5], v[2:3], off offset:512
	v_cvt_pk_bf16_f32 v2, v62, v63
	v_cvt_pk_bf16_f32 v3, v64, v65
	ds_bpermute_b32 v40, v40, v39
	global_store_dwordx2 v[4:5], v[2:3], off offset:1024
	v_cvt_pk_bf16_f32 v2, v66, v67
	v_cvt_pk_bf16_f32 v3, v68, v69
	global_store_dwordx2 v[4:5], v[2:3], off offset:1536
	v_cvt_pk_bf16_f32 v2, v70, v71
	v_cvt_pk_bf16_f32 v3, v72, v73
	global_store_dwordx2 v[4:5], v[2:3], off offset:2048
	v_cvt_pk_bf16_f32 v2, v74, v75
	v_cvt_pk_bf16_f32 v3, v76, v77
	global_store_dwordx2 v[4:5], v[2:3], off offset:2560
	v_cvt_pk_bf16_f32 v2, v78, v79
	v_cvt_pk_bf16_f32 v3, v80, v81
	global_store_dwordx2 v[4:5], v[2:3], off offset:3072
	v_cvt_pk_bf16_f32 v2, v82, v83
	v_cvt_pk_bf16_f32 v3, v84, v85
	global_store_dwordx2 v[4:5], v[2:3], off offset:3584
	s_and_saveexec_b64 s[18:19], s[2:3]
	s_cbranch_execz .LBB0_123
	s_waitcnt lgkmcnt(0)
	v_add_f32_e32 v2, v39, v40
	v_fmamk_f32 v2, v2, 0x39800000, v1
	v_mul_f32_e32 v3, 0x4f800000, v2
	v_cmp_gt_f32_e32 vcc, s40, v2
	s_nop 1
	v_cndmask_b32_e32 v2, v2, v3, vcc
	v_sqrt_f32_e32 v3, v2
	s_nop 0
	v_add_u32_e32 v4, -1, v3
	v_fma_f32 v6, -v4, v3, v2
	v_add_u32_e32 v5, 1, v3
	v_cmp_ge_f32_e64 s[4:5], 0, v6
	s_nop 1
	v_cndmask_b32_e64 v4, v3, v4, s[4:5]
	v_fma_f32 v3, -v5, v3, v2
	v_cmp_lt_f32_e64 s[4:5], 0, v3
	s_nop 1
	v_cndmask_b32_e64 v3, v4, v5, s[4:5]
	v_mul_f32_e32 v4, 0x37800000, v3
	v_cndmask_b32_e32 v3, v3, v4, vcc
	v_cmp_class_f32_e32 vcc, v2, v30
	s_nop 1
	v_cndmask_b32_e32 v2, v3, v2, vcc
	v_div_scale_f32 v3, s[4:5], v2, v2, 1.0
	v_rcp_f32_e32 v4, v3
	s_lshl_b64 s[4:5], s[16:17], 2
	s_add_u32 s4, s30, s4
	s_addc_u32 s5, s31, s5
	v_fma_f32 v5, -v3, v4, 1.0
	v_fmac_f32_e32 v4, v5, v4
	v_div_scale_f32 v5, vcc, 1.0, v2, 1.0
	v_mul_f32_e32 v6, v5, v4
	v_fma_f32 v7, -v3, v6, v5
	v_fmac_f32_e32 v6, v7, v4
	v_fma_f32 v3, -v3, v6, v5
	v_div_fmas_f32 v3, v3, v4, v6
	v_div_fixup_f32 v2, v3, v2, 1.0
	global_store_dword v23, v2, s[4:5]
	s_branch .LBB0_123

.LBB0_1068:
	s_ashr_i32 s26, s40, 5
	s_lshl_b32 s8, s26, 2
	s_add_i32 s52, s8, 0x2000
	s_lshl_b32 s8, s40, 6
	s_and_b32 s8, s8, 0x7c0
	v_or_b32_e32 v89, s8, v80
	s_mov_b64 s[8:9], -1
	s_and_b64 vcc, exec, s[10:11]
	s_cbranch_vccz .LBB0_1079
	v_readlane_b32 s72, v254, 28
	v_readlane_b32 s74, v254, 30
	v_readlane_b32 s75, v254, 31
	v_readlane_b32 s76, v254, 32
	v_readlane_b32 s77, v254, 33
	v_readlane_b32 s78, v254, 34
	v_readlane_b32 s79, v254, 35
	v_readlane_b32 s80, v254, 36
	v_readlane_b32 s81, v254, 37
	v_readlane_b32 s82, v254, 38
	v_readlane_b32 s83, v254, 39
	v_lshlrev_b32_e32 v72, 2, v89
	v_readlane_b32 s84, v254, 40
	v_readlane_b32 s85, v254, 41
	v_readlane_b32 s86, v254, 42
	v_readlane_b32 s87, v254, 43
	s_mov_b64 s[74:75], s[78:79]
	s_mov_b64 s[76:77], s[80:81]
	global_load_dwordx4 v[24:27], v72, s[14:15] nt
	global_load_dwordx4 v[10:13], v72, s[18:19] nt
	global_load_dwordx4 v[32:35], v72, s[70:71] nt
	s_mov_b64 s[78:79], s[82:83]
	s_mov_b64 s[80:81], s[84:85]
	s_mov_b64 s[82:83], s[86:87]
	global_load_dwordx4 v[28:31], v72, s[74:75] nt
	global_load_dwordx4 v[6:9], v72, s[76:77] nt
	global_load_dwordx4 v[2:5], v72, s[78:79] nt
	global_load_dwordx4 v[16:19], v72, s[80:81] nt
	global_load_dwordx4 v[20:23], v72, s[82:83] nt
	v_mov_b32_e32 v47, 0
	s_waitcnt vmcnt(8)
	v_mov_b32_e32 v63, 0
	v_mov_b32_e32 v62, 0
	v_mov_b32_e32 v46, 0
	v_mov_b32_e32 v45, 0
	v_mov_b32_e32 v44, 0
	v_mov_b32_e32 v65, 0
	v_mov_b32_e32 v64, 0
	v_mov_b32_e32 v15, 0
	v_mov_b32_e32 v14, 0
	v_mov_b32_e32 v39, 0
	v_mov_b32_e32 v38, 0
	v_mov_b32_e32 v37, 0
	v_mov_b32_e32 v36, 0
	v_mov_b32_e32 v43, 0
	v_mov_b32_e32 v42, 0
	v_mov_b32_e32 v41, 0
	s_waitcnt lgkmcnt(0)
	v_mov_b32_e32 v40, 0
	v_mov_b32_e32 v51, 0
	v_mov_b32_e32 v50, 0
	v_mov_b32_e32 v49, 0
	v_mov_b32_e32 v48, 0
	v_mov_b32_e32 v69, 0
	v_mov_b32_e32 v68, 0
	v_mov_b32_e32 v67, 0
	v_mov_b32_e32 v66, 0
	v_mov_b32_e32 v75, 0
	v_mov_b32_e32 v74, 0
	v_mov_b32_e32 v71, 0
	v_mov_b32_e32 v70, 0
	v_mov_b32_e32 v77, 0
	v_mov_b32_e32 v76, 0
	v_mov_b32_e32 v79, 0
	v_mov_b32_e32 v78, 0
	v_readlane_b32 s73, v254, 29
	s_and_saveexec_b64 s[8:9], s[2:3]
	s_cbranch_execz .LBB0_1076
	v_add_u32_e32 v62, s52, v52
	v_mov_b64_e32 v[14:15], s[20:21]
	v_mad_i64_i32 v[14:15], s[42:43], v62, s59, v[14:15]
	v_lshlrev_b32_e32 v54, 1, v89
	v_lshl_add_u64 v[64:65], v[14:15], 0, v[54:55]
	v_add_co_u32_e32 v14, vcc, 0x1000, v64
	s_mov_b32 s41, s49
	s_nop 0
	v_addc_co_u32_e32 v15, vcc, 0, v65, vcc
	v_add_co_u32_e32 v36, vcc, 0x2000, v64
	s_nop 1
	v_addc_co_u32_e32 v37, vcc, 0, v65, vcc
	global_load_dwordx2 v[46:47], v[64:65], off
	global_load_dwordx2 v[44:45], v[14:15], off
	s_nop 0
	global_load_dwordx2 v[14:15], v[36:37], off
	s_and_saveexec_b64 s[42:43], s[4:5]
	s_xor_b64 s[54:55], exec, s[42:43]
	s_cbranch_execz .LBB0_1073
	s_andn2_b64 vcc, exec, s[22:23]
	s_cbranch_vccnz .LBB0_1093
	v_readlane_b32 s72, v254, 12
	v_readlane_b32 s84, v254, 24
	v_readlane_b32 s85, v254, 25
	s_mul_hi_i32 s27, s26, 0x6700
	s_mulk_i32 s26, 0x6700
	s_mov_b64 s[48:49], s[84:85]
	s_add_u32 s26, s48, s26
	s_addc_u32 s27, s49, s27
	v_mov_b32_e32 v73, v55
	v_lshl_add_u64 v[36:37], s[26:27], 0, v[72:73]
	v_add_co_u32_e32 v38, vcc, 0x2000, v36
	global_load_dwordx4 v[48:51], v72, s[26:27] nt
	s_nop 0
	v_addc_co_u32_e32 v39, vcc, 0, v37, vcc
	v_add_co_u32_e32 v36, vcc, 0x4000, v36
	v_readlane_b32 s73, v254, 13
	s_nop 0
	v_addc_co_u32_e32 v37, vcc, 0, v37, vcc
	global_load_dwordx4 v[40:43], v[38:39], off nt
	s_nop 0
	global_load_dwordx4 v[36:39], v[36:37], off nt
	v_readlane_b32 s74, v254, 14
	v_readlane_b32 s75, v254, 15
	v_readlane_b32 s76, v254, 16
	v_readlane_b32 s77, v254, 17
	v_readlane_b32 s78, v254, 18
	v_readlane_b32 s79, v254, 19
	v_readlane_b32 s80, v254, 20
	v_readlane_b32 s81, v254, 21
	v_readlane_b32 s82, v254, 22
	v_readlane_b32 s83, v254, 23
	v_readlane_b32 s86, v254, 26
	v_readlane_b32 s87, v254, 27

.LBB0_1079:
	s_ashr_i32 s41, s40, 31
	v_mov_b32_e32 v26, 0
	s_lshl_b64 s[54:55], s[40:41], 12
	s_and_b64 vcc, exec, s[8:9]
	v_mov_b32_e32 v27, v26
	v_mov_b32_e32 v34, v26
	v_mov_b32_e32 v35, v26
	v_mov_b32_e32 v8, v26
	v_mov_b32_e32 v9, v26
	v_mov_b32_e32 v32, v26
	v_mov_b32_e32 v33, v26
	v_mov_b32_e32 v12, v26
	v_mov_b32_e32 v13, v26
	v_mov_b32_e32 v30, v26
	v_mov_b32_e32 v31, v26
	v_mov_b32_e32 v4, v26
	v_mov_b32_e32 v5, v26
	v_mov_b32_e32 v28, v26
	v_mov_b32_e32 v29, v26
	s_cbranch_vccz .LBB0_1083
	v_mov_b32_e32 v24, 0
	s_andn2_b64 vcc, exec, s[36:37]
	v_mov_b32_e32 v29, 0
	v_mov_b32_e32 v28, 0
	v_mov_b32_e32 v5, 0
	v_mov_b32_e32 v4, 0
	v_mov_b32_e32 v31, 0
	v_mov_b32_e32 v30, 0
	v_mov_b32_e32 v13, 0
	v_mov_b32_e32 v12, 0
	v_mov_b32_e32 v33, 0
	v_mov_b32_e32 v32, 0
	v_mov_b32_e32 v9, 0
	v_mov_b32_e32 v8, 0
	v_mov_b32_e32 v35, 0
	v_mov_b32_e32 v34, 0
	v_mov_b32_e32 v27, 0
	v_mov_b32_e32 v26, 0
	s_cbranch_vccnz .LBB0_1082
	v_lshl_add_u64 v[6:7], s[54:55], 2, v[58:59]
	global_load_dwordx4 v[10:13], v[6:7], off offset:272 nt
	global_load_dwordx4 v[2:5], v[6:7], off offset:16 nt
	global_load_dwordx4 v[14:17], v[6:7], off offset:256 nt
	s_nop 0
	global_load_dwordx4 v[6:9], v[6:7], off nt
	s_waitcnt vmcnt(3)
	v_mov_b32_e32 v29, v13
	s_waitcnt vmcnt(2)
	v_mov_b32_e32 v28, v5
	v_mov_b32_e32 v5, v12
	v_mov_b32_e32 v31, v11
	v_mov_b32_e32 v30, v3
	v_mov_b32_e32 v13, v10
	v_mov_b32_e32 v12, v2
	s_waitcnt vmcnt(1)
	v_mov_b32_e32 v33, v17
	s_waitcnt vmcnt(0)
	v_mov_b32_e32 v32, v9
	v_mov_b32_e32 v9, v16
	v_mov_b32_e32 v35, v15
	v_mov_b32_e32 v34, v7
	v_mov_b32_e32 v27, v14
	v_mov_b32_e32 v26, v6

.LBB0_1099:
	s_lshl_b32 s8, s36, 8
	s_and_b32 s14, s8, 0x300
	s_and_b32 s8, s36, -4
	s_addk_i32 s8, 0x2000
	s_ashr_i32 s9, s8, 31
	s_lshl_b64 s[10:11], s[8:9], 11
	s_add_u32 s10, s18, s10
	s_addc_u32 s11, s19, s11
	s_lshl_b32 s37, s14, 1
	s_add_u32 s10, s10, s37
	s_addc_u32 s11, s11, 0
	v_lshl_add_u64 v[2:3], s[10:11], 0, v[52:53]
	v_lshl_add_u64 v[34:35], v[2:3], 0, v[54:55]
	v_mov_b32_e32 v2, 0
	v_mov_b32_e32 v3, 0
	v_mov_b32_e32 v4, 0
	v_mov_b32_e32 v5, 0
	s_and_saveexec_b64 s[10:11], s[2:3]
	s_cbranch_execz .LBB0_1101
	global_load_dwordx4 v[2:5], v[34:35], off nt
.LBB0_1101:
	s_or_b64 exec, exec, s[10:11]
	v_mov_b32_e32 v6, 0
	v_mov_b32_e32 v10, 0
	v_mov_b32_e32 v11, 0
	v_mov_b32_e32 v12, 0
	v_mov_b32_e32 v13, 0
	s_and_saveexec_b64 s[10:11], s[2:3]
	s_cbranch_execz .LBB0_1103
	global_load_dwordx4 v[10:13], v[34:35], off offset:64 nt
.LBB0_1103:
	s_or_b64 exec, exec, s[10:11]
	v_mov_b32_e32 v7, 0
	v_mov_b32_e32 v8, 0
	v_mov_b32_e32 v9, 0
	s_and_saveexec_b64 s[10:11], s[2:3]
	s_cbranch_execz .LBB0_1105
	global_load_dwordx4 v[6:9], v[34:35], off offset:128 nt
.LBB0_1105:
	s_or_b64 exec, exec, s[10:11]
	v_mov_b32_e32 v14, 0
	v_mov_b32_e32 v18, 0
	v_mov_b32_e32 v19, 0
	v_mov_b32_e32 v20, 0
	v_mov_b32_e32 v21, 0
	s_and_saveexec_b64 s[10:11], s[2:3]
	s_cbranch_execz .LBB0_1107
	global_load_dwordx4 v[18:21], v[34:35], off offset:192 nt
.LBB0_1107:
	s_or_b64 exec, exec, s[10:11]
	v_mov_b32_e32 v15, 0
	v_mov_b32_e32 v16, 0
	v_mov_b32_e32 v17, 0
	s_and_saveexec_b64 s[10:11], s[2:3]
	s_cbranch_execz .LBB0_1109
	global_load_dwordx4 v[14:17], v[34:35], off offset:256 nt
.LBB0_1109:
	s_or_b64 exec, exec, s[10:11]
	v_mov_b32_e32 v22, 0
	v_mov_b32_e32 v26, 0
	v_mov_b32_e32 v27, 0
	v_mov_b32_e32 v28, 0
	v_mov_b32_e32 v29, 0
	s_and_saveexec_b64 s[10:11], s[2:3]
	s_cbranch_execz .LBB0_1111
	global_load_dwordx4 v[26:29], v[34:35], off offset:320 nt
.LBB0_1111:
	s_or_b64 exec, exec, s[10:11]
	v_mov_b32_e32 v23, 0
	v_mov_b32_e32 v24, 0
	v_mov_b32_e32 v25, 0
	s_and_saveexec_b64 s[10:11], s[2:3]
	s_cbranch_execz .LBB0_1113
	global_load_dwordx4 v[22:25], v[34:35], off offset:384 nt
.LBB0_1113:
	s_or_b64 exec, exec, s[10:11]
	v_mov_b32_e32 v30, 0
	v_mov_b32_e32 v31, 0
	v_mov_b32_e32 v32, 0
	v_mov_b32_e32 v33, 0
	s_and_saveexec_b64 s[10:11], s[2:3]
	s_cbranch_execz .LBB0_1115
	global_load_dwordx4 v[30:33], v[34:35], off offset:448 nt
.LBB0_1115:
	s_or_b64 exec, exec, s[10:11]
	s_ashr_i32 s10, s36, 2
	v_readlane_b32 s72, v254, 12
	s_ashr_i32 s11, s10, 31
	v_readlane_b32 s78, v254, 18
	v_readlane_b32 s79, v254, 19
	s_lshl_b64 s[10:11], s[10:11], 20
	s_mov_b64 s[42:43], s[78:79]
	s_add_u32 s15, s42, s10
	s_addc_u32 s26, s43, s11
	s_lshl_b32 s14, s14, 2
	s_add_u32 s14, s15, s14
	s_addc_u32 s15, s26, 0
	v_lshlrev_b32_e32 v38, 2, v40
	v_lshl_add_u64 v[58:59], s[14:15], 0, v[38:39]
	v_lshl_add_u64 v[118:119], v[58:59], 0, v[42:43]
	global_load_dwordx4 v[34:37], v[118:119], off nt
	global_load_dwordx4 v[62:65], v[118:119], off offset:16 nt
	global_load_dwordx4 v[66:69], v[118:119], off offset:128 nt
	global_load_dwordx4 v[70:73], v[118:119], off offset:144 nt
	global_load_dwordx4 v[74:77], v[118:119], off offset:256 nt
	global_load_dwordx4 v[78:81], v[118:119], off offset:272 nt
	global_load_dwordx4 v[82:85], v[118:119], off offset:384 nt
	global_load_dwordx4 v[86:89], v[118:119], off offset:400 nt
	global_load_dwordx4 v[90:93], v[118:119], off offset:512 nt
	global_load_dwordx4 v[94:97], v[118:119], off offset:528 nt
	global_load_dwordx4 v[98:101], v[118:119], off offset:640 nt
	global_load_dwordx4 v[102:105], v[118:119], off offset:656 nt
	global_load_dwordx4 v[106:109], v[118:119], off offset:768 nt
	global_load_dwordx4 v[110:113], v[118:119], off offset:784 nt
	global_load_dwordx4 v[114:117], v[118:119], off offset:896 nt
	s_nop 0
	global_load_dwordx4 v[118:121], v[118:119], off offset:912 nt
	v_readlane_b32 s73, v254, 13
	v_readlane_b32 s74, v254, 14
	v_readlane_b32 s75, v254, 15
	v_readlane_b32 s76, v254, 16
	v_readlane_b32 s77, v254, 17
	v_readlane_b32 s80, v254, 20
	v_readlane_b32 s81, v254, 21
	v_readlane_b32 s82, v254, 22
	v_readlane_b32 s83, v254, 23
	v_readlane_b32 s84, v254, 24
	v_readlane_b32 s85, v254, 25
	v_readlane_b32 s86, v254, 26
	v_readlane_b32 s87, v254, 27
	s_waitcnt vmcnt(15)
	v_cvt_pk_bf16_f32 v34, v34, v35
	v_cvt_pk_bf16_f32 v35, v36, v37
	s_waitcnt vmcnt(14)
	v_cvt_pk_bf16_f32 v36, v62, v63
	v_cvt_pk_bf16_f32 v37, v64, v65
	s_waitcnt vmcnt(13)
	v_cvt_pk_bf16_f32 v62, v66, v67
	v_cvt_pk_bf16_f32 v63, v68, v69
	s_waitcnt vmcnt(12)
	v_cvt_pk_bf16_f32 v64, v70, v71
	v_cvt_pk_bf16_f32 v65, v72, v73
	v_mfma_f32_16x16x32_bf16 v[34:37], v[34:37], v[2:5], 0
	s_waitcnt vmcnt(11)
	v_cvt_pk_bf16_f32 v66, v74, v75
	v_cvt_pk_bf16_f32 v67, v76, v77
	s_waitcnt vmcnt(10)
	v_cvt_pk_bf16_f32 v68, v78, v79
	v_cvt_pk_bf16_f32 v69, v80, v81
	v_mfma_f32_16x16x32_bf16 v[34:37], v[62:65], v[10:13], v[34:37]
	s_waitcnt vmcnt(9)
	v_cvt_pk_bf16_f32 v70, v82, v83
	v_cvt_pk_bf16_f32 v71, v84, v85
	s_waitcnt vmcnt(8)
	v_cvt_pk_bf16_f32 v72, v86, v87
	v_cvt_pk_bf16_f32 v73, v88, v89
	v_mfma_f32_16x16x32_bf16 v[34:37], v[66:69], v[6:9], v[34:37]
	s_waitcnt vmcnt(7)
	v_cvt_pk_bf16_f32 v62, v90, v91
	v_cvt_pk_bf16_f32 v63, v92, v93
	s_waitcnt vmcnt(6)
	v_cvt_pk_bf16_f32 v64, v94, v95
	v_cvt_pk_bf16_f32 v65, v96, v97
	v_mfma_f32_16x16x32_bf16 v[34:37], v[70:73], v[18:21], v[34:37]
	s_waitcnt vmcnt(5)
	v_cvt_pk_bf16_f32 v66, v98, v99
	v_cvt_pk_bf16_f32 v67, v100, v101
	s_waitcnt vmcnt(4)
	v_cvt_pk_bf16_f32 v68, v102, v103
	v_cvt_pk_bf16_f32 v69, v104, v105
	v_mfma_f32_16x16x32_bf16 v[34:37], v[62:65], v[14:17], v[34:37]
	s_waitcnt vmcnt(3)
	v_cvt_pk_bf16_f32 v70, v106, v107
	v_cvt_pk_bf16_f32 v71, v108, v109
	s_waitcnt vmcnt(2)
	v_cvt_pk_bf16_f32 v72, v110, v111
	v_cvt_pk_bf16_f32 v73, v112, v113
	v_mfma_f32_16x16x32_bf16 v[34:37], v[66:69], v[26:29], v[34:37]
	s_waitcnt vmcnt(1)
	v_cvt_pk_bf16_f32 v62, v114, v115
	v_cvt_pk_bf16_f32 v63, v116, v117
	s_waitcnt vmcnt(0)
	v_cvt_pk_bf16_f32 v64, v118, v119
	v_cvt_pk_bf16_f32 v65, v120, v121
	v_mfma_f32_16x16x32_bf16 v[34:37], v[70:73], v[22:25], v[34:37]
	s_nop 0
	v_mfma_f32_16x16x32_bf16 v[34:37], v[62:65], v[30:33], v[34:37]
	s_and_saveexec_b64 s[14:15], s[2:3]
	s_nop 6
	ds_write_b128 v60, v[34:37]
	s_or_b64 exec, exec, s[14:15]
	v_lshl_add_u64 v[58:59], v[58:59], 0, v[44:45]
	global_load_dwordx4 v[34:37], v[58:59], off nt
	global_load_dwordx4 v[62:65], v[58:59], off offset:16 nt
	global_load_dwordx4 v[66:69], v[58:59], off offset:128 nt
	global_load_dwordx4 v[70:73], v[58:59], off offset:144 nt
	global_load_dwordx4 v[74:77], v[58:59], off offset:256 nt
	global_load_dwordx4 v[78:81], v[58:59], off offset:272 nt
	global_load_dwordx4 v[82:85], v[58:59], off offset:384 nt
	global_load_dwordx4 v[86:89], v[58:59], off offset:400 nt
	global_load_dwordx4 v[90:93], v[58:59], off offset:512 nt
	global_load_dwordx4 v[94:97], v[58:59], off offset:528 nt
	global_load_dwordx4 v[98:101], v[58:59], off offset:640 nt
	global_load_dwordx4 v[102:105], v[58:59], off offset:656 nt
	global_load_dwordx4 v[106:109], v[58:59], off offset:768 nt
	global_load_dwordx4 v[110:113], v[58:59], off offset:784 nt
	global_load_dwordx4 v[114:117], v[58:59], off offset:896 nt
	global_load_dwordx4 v[118:121], v[58:59], off offset:912 nt
	s_waitcnt vmcnt(15)
	v_cvt_pk_bf16_f32 v34, v34, v35
	v_cvt_pk_bf16_f32 v35, v36, v37
	s_waitcnt vmcnt(14)
	v_cvt_pk_bf16_f32 v36, v62, v63
	v_cvt_pk_bf16_f32 v37, v64, v65
	s_waitcnt vmcnt(13)
	v_cvt_pk_bf16_f32 v62, v66, v67
	v_cvt_pk_bf16_f32 v63, v68, v69
	s_waitcnt vmcnt(12)
	v_cvt_pk_bf16_f32 v64, v70, v71
	v_cvt_pk_bf16_f32 v65, v72, v73
	v_mfma_f32_16x16x32_bf16 v[2:5], v[34:37], v[2:5], 0
	s_waitcnt vmcnt(11)
	v_cvt_pk_bf16_f32 v66, v74, v75
	v_cvt_pk_bf16_f32 v67, v76, v77
	s_waitcnt vmcnt(10)
	v_cvt_pk_bf16_f32 v68, v78, v79
	v_cvt_pk_bf16_f32 v69, v80, v81
	v_mfma_f32_16x16x32_bf16 v[2:5], v[62:65], v[10:13], v[2:5]
	s_waitcnt vmcnt(9)
	v_cvt_pk_bf16_f32 v70, v82, v83
	v_cvt_pk_bf16_f32 v71, v84, v85
	s_waitcnt vmcnt(8)
	v_cvt_pk_bf16_f32 v72, v86, v87
	v_cvt_pk_bf16_f32 v73, v88, v89
	v_mfma_f32_16x16x32_bf16 v[2:5], v[66:69], v[6:9], v[2:5]
	s_waitcnt vmcnt(7)
	v_cvt_pk_bf16_f32 v10, v90, v91
	v_cvt_pk_bf16_f32 v11, v92, v93
	s_waitcnt vmcnt(6)
	v_cvt_pk_bf16_f32 v12, v94, v95
	v_cvt_pk_bf16_f32 v13, v96, v97
	v_mfma_f32_16x16x32_bf16 v[2:5], v[70:73], v[18:21], v[2:5]
	s_waitcnt vmcnt(5)
	v_cvt_pk_bf16_f32 v6, v98, v99
	v_cvt_pk_bf16_f32 v7, v100, v101
	s_waitcnt vmcnt(4)
	v_cvt_pk_bf16_f32 v8, v102, v103
	v_cvt_pk_bf16_f32 v9, v104, v105
	v_mfma_f32_16x16x32_bf16 v[2:5], v[10:13], v[14:17], v[2:5]
	s_waitcnt vmcnt(3)
	v_cvt_pk_bf16_f32 v18, v106, v107
	v_cvt_pk_bf16_f32 v19, v108, v109
	s_waitcnt vmcnt(2)
	v_cvt_pk_bf16_f32 v20, v110, v111
	v_cvt_pk_bf16_f32 v21, v112, v113
	v_mfma_f32_16x16x32_bf16 v[2:5], v[6:9], v[26:29], v[2:5]
	s_waitcnt vmcnt(1)
	v_cvt_pk_bf16_f32 v6, v114, v115
	v_cvt_pk_bf16_f32 v7, v116, v117
	s_waitcnt vmcnt(0)
	v_cvt_pk_bf16_f32 v8, v118, v119
	v_cvt_pk_bf16_f32 v9, v120, v121
	v_mfma_f32_16x16x32_bf16 v[2:5], v[18:21], v[22:25], v[2:5]
	s_nop 0
	v_mfma_f32_16x16x32_bf16 v[2:5], v[6:9], v[30:33], v[2:5]
	s_and_saveexec_b64 s[14:15], s[2:3]
	s_nop 6
	ds_write_b128 v60, v[2:5] offset:64
	s_or_b64 exec, exec, s[14:15]
	s_andn2_b64 vcc, exec, s[0:1]
	s_waitcnt lgkmcnt(0)
	s_barrier
	s_cbranch_vccnz .LBB0_1123
	v_add_u32_e32 v10, s21, v46
	ds_read_b128 v[2:5], v10
	v_and_b32_e32 v6, 64, v61
	v_xor_b32_e32 v7, 1, v61
	v_add_u32_e32 v6, 64, v6
	v_cmp_lt_i32_e32 vcc, v7, v6
	s_waitcnt lgkmcnt(0)
	v_max_f32_e32 v8, v5, v5
	v_max_f32_e32 v9, v4, v4
	v_max_f32_e32 v8, v9, v8
	v_cndmask_b32_e32 v7, v61, v7, vcc
	v_max3_f32 v8, v2, v3, v8
	v_lshlrev_b32_e32 v11, 2, v7
	ds_bpermute_b32 v7, v11, v8
	v_xor_b32_e32 v9, 2, v61
	v_cmp_lt_i32_e32 vcc, v9, v6
	s_waitcnt lgkmcnt(0)
	v_max_f32_e32 v7, v7, v7
	v_max_f32_e32 v7, v8, v7
	v_cndmask_b32_e32 v8, v61, v9, vcc
	v_lshlrev_b32_e32 v12, 2, v8
	ds_bpermute_b32 v8, v12, v7
	v_xor_b32_e32 v9, 4, v61
	v_cmp_lt_i32_e32 vcc, v9, v6
	s_waitcnt lgkmcnt(0)
	v_max_f32_e32 v8, v8, v8
	v_max_f32_e32 v7, v7, v8
	v_cndmask_b32_e32 v8, v61, v9, vcc
	v_lshlrev_b32_e32 v13, 2, v8
	ds_bpermute_b32 v8, v13, v7
	v_xor_b32_e32 v9, 8, v61
	v_cmp_lt_i32_e32 vcc, v9, v6
	s_waitcnt lgkmcnt(0)
	v_max_f32_e32 v8, v8, v8
	v_max_f32_e32 v7, v7, v8
	v_cndmask_b32_e32 v8, v61, v9, vcc
	v_lshlrev_b32_e32 v14, 2, v8
	ds_bpermute_b32 v8, v14, v7
	v_xor_b32_e32 v9, 16, v61
	v_cmp_lt_i32_e32 vcc, v9, v6
	s_waitcnt lgkmcnt(0)
	v_max_f32_e32 v8, v8, v8
	v_max_f32_e32 v7, v7, v8
	v_cndmask_b32_e32 v8, v61, v9, vcc
	v_lshlrev_b32_e32 v15, 2, v8
	ds_bpermute_b32 v8, v15, v7
	v_xor_b32_e32 v9, 32, v61
	v_cmp_lt_i32_e32 vcc, v9, v6
	s_waitcnt lgkmcnt(0)
	v_max_f32_e32 v8, v8, v8
	v_cndmask_b32_e32 v6, v61, v9, vcc
	v_max_f32_e32 v7, v7, v8
	v_lshlrev_b32_e32 v16, 2, v6
	ds_bpermute_b32 v6, v16, v7
	s_waitcnt lgkmcnt(0)
	v_max_f32_e32 v6, v6, v6
	v_max_f32_e32 v9, v7, v6
	v_sub_f32_e32 v2, v2, v9
	v_sub_f32_e32 v3, v3, v9
	v_exp_f32_e32 v6, v2
	v_exp_f32_e32 v7, v3
	v_sub_f32_e32 v2, v4, v9
	v_exp_f32_e32 v8, v2
	v_sub_f32_e32 v2, v5, v9
	v_exp_f32_e32 v9, v2
	v_add_f32_e32 v2, 0, v6
	v_add_f32_e32 v2, v7, v2
	v_add_f32_e32 v2, v8, v2
	v_add_f32_e32 v2, v9, v2
	ds_bpermute_b32 v3, v11, v2
	ds_write_b128 v10, v[6:9]
	s_waitcnt lgkmcnt(1)
	v_add_f32_e32 v2, v2, v3
	ds_bpermute_b32 v3, v12, v2
	s_waitcnt lgkmcnt(0)
	v_add_f32_e32 v2, v2, v3
	ds_bpermute_b32 v3, v13, v2
	s_waitcnt lgkmcnt(0)
	v_add_f32_e32 v2, v2, v3
	ds_bpermute_b32 v3, v14, v2
	s_waitcnt lgkmcnt(0)
	v_add_f32_e32 v2, v2, v3
	ds_bpermute_b32 v3, v15, v2
	s_waitcnt lgkmcnt(0)
	v_add_f32_e32 v2, v2, v3
	ds_bpermute_b32 v3, v16, v2
	s_and_saveexec_b64 s[14:15], s[4:5]
	s_cbranch_execz .LBB0_1122
	s_waitcnt lgkmcnt(0)
	v_add_f32_e32 v2, v2, v3
	v_div_scale_f32 v3, s[26:27], v2, v2, 1.0
	v_rcp_f32_e32 v4, v3
	v_div_scale_f32 v5, vcc, 1.0, v2, 1.0
	v_fma_f32 v6, -v3, v4, 1.0
	v_fmac_f32_e32 v4, v6, v4
	v_mul_f32_e32 v6, v5, v4
	v_fma_f32 v7, -v3, v6, v5
	v_fmac_f32_e32 v6, v7, v4
	v_fma_f32 v3, -v3, v6, v5
	v_div_fmas_f32 v3, v3, v4, v6
	v_div_fixup_f32 v2, v3, v2, 1.0
	v_mov_b32_e32 v3, s29
	ds_write_b32 v3, v2 offset:36864

.LBB0_1124:
	v_add_co_u32_e32 v32, vcc, s30, v18
	global_load_dwordx4 v[20:23], v[18:19], off offset:-4096 nt
	global_load_dwordx4 v[24:27], v[18:19], off nt
	v_addc_co_u32_e32 v33, vcc, -1, v19, vcc
	v_add_co_u32_e32 v36, vcc, s31, v18
	v_mov_b32_e32 v38, s11
	s_nop 0
	v_addc_co_u32_e32 v37, vcc, -1, v19, vcc
	v_add_co_u32_e32 v58, vcc, s33, v18
	s_add_i32 s10, s10, 8
	s_nop 0
	v_addc_co_u32_e32 v59, vcc, -1, v19, vcc
	global_load_dwordx4 v[28:31], v[32:33], off offset:-4096 nt
	s_nop 0
	global_load_dwordx4 v[32:35], v[32:33], off nt
	s_nop 0
	global_load_dwordx4 v[62:65], v[36:37], off offset:-4096 nt
	global_load_dwordx4 v[66:69], v[36:37], off nt
	global_load_dwordx4 v[70:73], v[58:59], off offset:-4096 nt
	global_load_dwordx4 v[74:77], v[58:59], off nt
	ds_read_b128 v[78:81], v38
	ds_read_b128 v[82:85], v38 offset:16
	ds_read_b128 v[86:89], v38 offset:1024
	ds_read_b128 v[90:93], v38 offset:1040
	ds_read_b128 v[94:97], v38 offset:2048
	ds_read_b128 v[98:101], v38 offset:2064
	ds_read_b128 v[102:105], v38 offset:3072
	ds_read_b128 v[106:109], v38 offset:3088
	s_waitcnt lgkmcnt(7)
	v_mov_b32_e32 v36, v81
	s_waitcnt lgkmcnt(5)
	v_mov_b32_e32 v38, v89
	s_waitcnt lgkmcnt(3)
	v_mov_b32_e32 v58, v97
	s_waitcnt lgkmcnt(1)
	v_mov_b32_e32 v110, v105
	s_add_i32 s11, s11, 32
	v_mov_b32_e32 v112, v85
	v_mov_b32_e32 v114, v93
	v_mov_b32_e32 v116, v101
	s_waitcnt lgkmcnt(0)
	v_mov_b32_e32 v118, v109
	v_lshl_add_u64 v[18:19], v[18:19], 0, s[6:7]
	s_cmp_lt_u32 s10, 28
	s_waitcnt vmcnt(5)
	v_pk_fma_f32 v[4:5], v[78:79], v[30:31], v[4:5] op_sel_hi:[0,1,1]
	v_pk_fma_f32 v[2:3], v[78:79], v[28:29], v[2:3] op_sel_hi:[0,1,1]
	v_pk_fma_f32 v[8:9], v[86:87], v[30:31], v[8:9] op_sel_hi:[0,1,1]
	v_pk_fma_f32 v[6:7], v[86:87], v[28:29], v[6:7] op_sel_hi:[0,1,1]
	v_pk_fma_f32 v[12:13], v[94:95], v[30:31], v[12:13] op_sel_hi:[0,1,1]
	v_pk_fma_f32 v[10:11], v[94:95], v[28:29], v[10:11] op_sel_hi:[0,1,1]
	v_pk_fma_f32 v[16:17], v[30:31], v[102:103], v[16:17] op_sel_hi:[1,0,1]
	v_pk_fma_f32 v[14:15], v[28:29], v[102:103], v[14:15] op_sel_hi:[1,0,1]
	s_waitcnt vmcnt(4)
	v_pk_fma_f32 v[4:5], v[78:79], v[34:35], v[4:5] op_sel:[1,0,0]
	v_pk_fma_f32 v[2:3], v[78:79], v[32:33], v[2:3] op_sel:[1,0,0]
	v_pk_fma_f32 v[8:9], v[86:87], v[34:35], v[8:9] op_sel:[1,0,0]
	v_pk_fma_f32 v[6:7], v[86:87], v[32:33], v[6:7] op_sel:[1,0,0]
	v_pk_fma_f32 v[12:13], v[94:95], v[34:35], v[12:13] op_sel:[1,0,0]
	v_pk_fma_f32 v[10:11], v[94:95], v[32:33], v[10:11] op_sel:[1,0,0]
	v_pk_fma_f32 v[16:17], v[102:103], v[34:35], v[16:17] op_sel:[1,0,0]
	v_pk_fma_f32 v[14:15], v[102:103], v[32:33], v[14:15] op_sel:[1,0,0]
	s_waitcnt vmcnt(3)
	v_pk_fma_f32 v[4:5], v[80:81], v[64:65], v[4:5] op_sel_hi:[0,1,1]
	v_pk_fma_f32 v[2:3], v[80:81], v[62:63], v[2:3] op_sel_hi:[0,1,1]
	v_pk_fma_f32 v[8:9], v[88:89], v[64:65], v[8:9] op_sel_hi:[0,1,1]
	v_pk_fma_f32 v[6:7], v[88:89], v[62:63], v[6:7] op_sel_hi:[0,1,1]
	v_pk_fma_f32 v[12:13], v[96:97], v[64:65], v[12:13] op_sel_hi:[0,1,1]
	v_pk_fma_f32 v[10:11], v[96:97], v[62:63], v[10:11] op_sel_hi:[0,1,1]
	v_pk_fma_f32 v[16:17], v[104:105], v[64:65], v[16:17] op_sel_hi:[0,1,1]
	v_pk_fma_f32 v[14:15], v[104:105], v[62:63], v[14:15] op_sel_hi:[0,1,1]
	s_waitcnt vmcnt(2)
	v_pk_fma_f32 v[4:5], v[36:37], v[68:69], v[4:5] op_sel_hi:[0,1,1]
	v_pk_fma_f32 v[2:3], v[36:37], v[66:67], v[2:3] op_sel_hi:[0,1,1]
	v_pk_fma_f32 v[8:9], v[38:39], v[68:69], v[8:9] op_sel_hi:[0,1,1]
	v_pk_fma_f32 v[6:7], v[38:39], v[66:67], v[6:7] op_sel_hi:[0,1,1]
	v_pk_fma_f32 v[12:13], v[58:59], v[68:69], v[12:13] op_sel_hi:[0,1,1]
	v_pk_fma_f32 v[10:11], v[58:59], v[66:67], v[10:11] op_sel_hi:[0,1,1]
	v_pk_fma_f32 v[16:17], v[110:111], v[68:69], v[16:17] op_sel_hi:[0,1,1]
	v_pk_fma_f32 v[14:15], v[110:111], v[66:67], v[14:15] op_sel_hi:[0,1,1]
	s_waitcnt vmcnt(1)
	v_pk_fma_f32 v[4:5], v[82:83], v[72:73], v[4:5] op_sel_hi:[0,1,1]
	v_pk_fma_f32 v[2:3], v[82:83], v[70:71], v[2:3] op_sel_hi:[0,1,1]
	v_pk_fma_f32 v[8:9], v[90:91], v[72:73], v[8:9] op_sel_hi:[0,1,1]
	v_pk_fma_f32 v[6:7], v[90:91], v[70:71], v[6:7] op_sel_hi:[0,1,1]
	v_pk_fma_f32 v[12:13], v[98:99], v[72:73], v[12:13] op_sel_hi:[0,1,1]
	v_pk_fma_f32 v[10:11], v[98:99], v[70:71], v[10:11] op_sel_hi:[0,1,1]
	v_pk_fma_f32 v[16:17], v[72:73], v[106:107], v[16:17] op_sel_hi:[1,0,1]
	v_pk_fma_f32 v[14:15], v[70:71], v[106:107], v[14:15] op_sel_hi:[1,0,1]
	s_waitcnt vmcnt(0)
	v_pk_fma_f32 v[4:5], v[82:83], v[76:77], v[4:5] op_sel:[1,0,0]
	v_pk_fma_f32 v[2:3], v[82:83], v[74:75], v[2:3] op_sel:[1,0,0]
	v_pk_fma_f32 v[8:9], v[90:91], v[76:77], v[8:9] op_sel:[1,0,0]
	v_pk_fma_f32 v[6:7], v[90:91], v[74:75], v[6:7] op_sel:[1,0,0]
	v_pk_fma_f32 v[12:13], v[98:99], v[76:77], v[12:13] op_sel:[1,0,0]
	v_pk_fma_f32 v[10:11], v[98:99], v[74:75], v[10:11] op_sel:[1,0,0]
	v_pk_fma_f32 v[16:17], v[106:107], v[76:77], v[16:17] op_sel:[1,0,0]
	v_pk_fma_f32 v[14:15], v[106:107], v[74:75], v[14:15] op_sel:[1,0,0]
	v_pk_fma_f32 v[4:5], v[84:85], v[22:23], v[4:5] op_sel_hi:[0,1,1]
	v_pk_fma_f32 v[2:3], v[84:85], v[20:21], v[2:3] op_sel_hi:[0,1,1]
	v_pk_fma_f32 v[8:9], v[92:93], v[22:23], v[8:9] op_sel_hi:[0,1,1]
	v_pk_fma_f32 v[6:7], v[92:93], v[20:21], v[6:7] op_sel_hi:[0,1,1]
	v_pk_fma_f32 v[12:13], v[100:101], v[22:23], v[12:13] op_sel_hi:[0,1,1]
	v_pk_fma_f32 v[10:11], v[100:101], v[20:21], v[10:11] op_sel_hi:[0,1,1]
	v_pk_fma_f32 v[16:17], v[108:109], v[22:23], v[16:17] op_sel_hi:[0,1,1]
	v_pk_fma_f32 v[14:15], v[108:109], v[20:21], v[14:15] op_sel_hi:[0,1,1]
	v_pk_fma_f32 v[4:5], v[112:113], v[26:27], v[4:5] op_sel_hi:[0,1,1]
	v_pk_fma_f32 v[2:3], v[112:113], v[24:25], v[2:3] op_sel_hi:[0,1,1]
	v_pk_fma_f32 v[8:9], v[114:115], v[26:27], v[8:9] op_sel_hi:[0,1,1]
	v_pk_fma_f32 v[6:7], v[114:115], v[24:25], v[6:7] op_sel_hi:[0,1,1]
	v_pk_fma_f32 v[12:13], v[116:117], v[26:27], v[12:13] op_sel_hi:[0,1,1]
	v_pk_fma_f32 v[10:11], v[116:117], v[24:25], v[10:11] op_sel_hi:[0,1,1]
	v_pk_fma_f32 v[16:17], v[118:119], v[26:27], v[16:17] op_sel_hi:[0,1,1]
	v_pk_fma_f32 v[14:15], v[118:119], v[24:25], v[14:15] op_sel_hi:[0,1,1]
	s_cbranch_scc1 .LBB0_1124
	v_add_u32_e32 v18, s22, v46
	ds_write_b128 v18, v[2:5] offset:4096
	ds_write_b128 v18, v[6:9] offset:5120
	ds_write_b128 v18, v[10:13] offset:6144
	ds_write_b128 v18, v[14:17] offset:7168
	s_waitcnt lgkmcnt(0)
	s_barrier
	ds_read2st64_b64 v[2:5], v41 offset0:8 offset1:16
	ds_read2st64_b64 v[6:9], v41 offset0:24 offset1:32
	ds_read2st64_b64 v[10:13], v41 offset0:40 offset1:48
	s_lshl_b64 s[8:9], s[8:9], 13
	s_add_u32 s8, s23, s8
	s_waitcnt lgkmcnt(2)
	v_pk_add_f32 v[2:3], v[2:3], 0 op_sel_hi:[1,0]
	s_addc_u32 s9, s24, s9
	v_pk_add_f32 v[14:15], v[2:3], v[4:5]
	ds_read2st64_b64 v[2:5], v41 offset0:56 offset1:64
	s_waitcnt lgkmcnt(2)
	v_pk_add_f32 v[6:7], v[14:15], v[6:7]
	s_add_u32 s8, s8, s37
	v_pk_add_f32 v[6:7], v[6:7], v[8:9]
	s_addc_u32 s9, s9, 0
	s_waitcnt lgkmcnt(1)
	v_pk_add_f32 v[6:7], v[6:7], v[10:11]
	v_mov_b32_e32 v57, v39
	v_pk_add_f32 v[6:7], v[6:7], v[12:13]
	s_add_i32 s36, s36, s13
	s_waitcnt lgkmcnt(0)
	v_pk_add_f32 v[2:3], v[6:7], v[2:3]
	s_add_i32 s25, s25, s28
	v_pk_add_f32 v[2:3], v[2:3], v[4:5]
	ds_read_b32 v4, v47 offset:36864
	s_cmpk_gt_i32 s36, 0x1ff
	s_waitcnt lgkmcnt(0)
	v_pk_mul_f32 v[2:3], v[2:3], v[4:5] op_sel_hi:[1,0]
	s_nop 0
	v_cvt_pk_bf16_f32 v4, v2, v3
	v_lshl_add_u64 v[2:3], s[8:9], 0, v[48:49]
	v_lshl_add_u64 v[2:3], v[2:3], 0, v[56:57]
	global_store_dword v[2:3], v4, off
	s_barrier
	s_cbranch_scc0 .LBB0_1099
